# attention: PV made P-fragment-major so each stage's exp/sum/pack issues under the previous stage's MFMAs; packed f32 adds split into scalar ops
# baseline (speedup 1.0000x reference)
; #define LAS __attribute__((address_space(3)))
; __device__ __forceinline__ void attn_unit(Frame& F, int b, int h, int qb, const bf16* QKVU, bf16* ATT, float lam, const float* subln_g, const unsigned* kmaxw) {
;     ...
;         const int kv0 = 64 * t;
;         if (!wdone && kv0 <= qw0 + 31) {
;             const LAS unsigned char* Kb = lds + slot * 32768; const LAS unsigned char* Vb = Kb + 16384;
;             f32x16 p0, p1;
;             { const float base = slope2 * (float)(kv0 - q0) - m_run;
; #pragma unroll
;               for (int r = 0; r < 16; ++r) { p0[r] = ab[r] + base; p1[r] = p0[r] + 32.f * slope2; } }
;             __builtin_amdgcn_s_setprio(1);
; #pragma unroll
;             for (int d0 = 0; d0 < 4; ++d0) { const bf16x8 k0 = *(const LAS bf16x8*)(Kb + koff[d0]), k1 = *(const LAS bf16x8*)(Kb + 8192 + koff[d0]);
;                 p0 = __builtin_amdgcn_mfma_f32_32x32x16_bf16(k0, qr[d0], p0, 0, 0, 0); p1 = __builtin_amdgcn_mfma_f32_32x32x16_bf16(k1, qr[d0], p1, 0, 0, 0); }
;             __builtin_amdgcn_s_setprio(0);
;             if (kv0 + 63 > qw0) { const int qpos = qw0 + r32;
; #pragma unroll
;                 for (int r = 0; r < 16; ++r) { const int kv = kv0 + crow(r, hi); if (kv > qpos) p0[r] = -INFINITY; if (kv + 32 > qpos) p1[r] = -INFINITY; } }
;             float mx = fmaxf(fmaxf(p0[0], p0[1]), p1[0]), mx2 = fmaxf(fmaxf(p0[2], p0[3]), p1[1]);
;             mx = fmaxf(fmaxf(mx, p1[2]), p1[3]);
; #pragma unroll
;             for (int r = 4; r < 16; r += 4) { mx = fmaxf(fmaxf(mx, p0[r]), p0[r + 1]); mx2 = fmaxf(fmaxf(mx2, p0[r + 2]), p0[r + 3]); mx = fmaxf(fmaxf(mx, p1[r]), p1[r + 1]); mx2 = fmaxf(fmaxf(mx2, p1[r + 2]), p1[r + 3]); }
;             mx = fmaxf(mx, mx2);
;             mx = fmaxf(mx, __shfl_xor(mx, 32));
;             bool sub = false; float delta = 0.f;
;             if (!started) { delta = mx; started = true; sub = true; }
;             else if (__any(mx > THR_RESC)) { delta = fmaxf(mx, 0.f); sub = true; const float f = __builtin_amdgcn_exp2f(-delta); l_sum *= f;
; #pragma unroll
;                 for (int c = 0; c < 4; ++c)
; #pragma unroll
;                     for (int r = 0; r < 16; ++r) o[c][r] *= f; }
;             if (sub) { m_run += delta;
; #pragma unroll
;                 for (int r = 0; r < 16; ++r) { p0[r] -= delta; p1[r] -= delta; } }
;             float ls = 0.f, ls2 = 0.f;
; #pragma unroll
.LBB0_520:
	s_xor_b64 s[12:13], s[12:13], -1
	s_andn2_b64 vcc, exec, s[12:13]
	s_mov_b64 s[12:13], -1
	s_cbranch_vccnz .LBB0_530
	s_add_i32 s22, s33, s67
	s_cmp_gt_u32 s22, s9
	s_mov_b64 s[12:13], 0
	s_cbranch_scc1 .LBB0_530
	v_cvt_f32_i32_e32 v66, s67
	s_lshl_b32 s12, s66, 15
	v_mov_b32_e32 v175, v174
	s_add_i32 s12, s12, 0
	v_fma_f32 v80, v114, v66, -v176
	v_add_f32_e32 v66, v158, v80
	v_add_f32_e32 v67, v159, v80
	v_add_f32_e32 v68, v160, v80
	v_add_f32_e32 v69, v161, v80
	v_add_f32_e32 v70, v162, v80
	v_add_f32_e32 v71, v163, v80
	v_add_f32_e32 v72, v164, v80
	v_add_f32_e32 v73, v165, v80
	v_add_f32_e32 v74, v166, v80
	v_add_f32_e32 v75, v167, v80
	v_add_f32_e32 v76, v168, v80
	v_add_f32_e32 v77, v169, v80
	v_add_f32_e32 v78, v170, v80
	v_add_f32_e32 v79, v171, v80
	v_add_f32_e32 v81, v173, v80
	v_add_f32_e32 v80, v172, v80
	v_add_f32_e32 v94, v174, v78
	v_add_f32_e32 v95, v175, v79
	v_add_f32_e32 v96, v174, v80
	v_add_f32_e32 v97, v175, v81
	v_add_f32_e32 v92, v174, v76
	v_add_f32_e32 v93, v175, v77
	v_add_f32_e32 v90, v174, v74
	v_add_f32_e32 v91, v175, v75
	v_add_f32_e32 v88, v174, v72
	v_add_f32_e32 v89, v175, v73
	v_add_f32_e32 v86, v174, v70
	v_add_f32_e32 v87, v175, v71
	v_add_f32_e32 v84, v174, v68
	v_add_f32_e32 v85, v175, v69
	v_add_f32_e32 v82, v178, v66
	v_add_f32_e32 v83, v179, v67
	s_setprio 1
	s_waitcnt lgkmcnt(0)
	v_mfma_f32_32x32x16_bf16 v[66:81], v[200:203], v[98:101], v[66:81]
	v_mfma_f32_32x32x16_bf16 v[82:97], v[204:207], v[98:101], v[82:97]
	v_mfma_f32_32x32x16_bf16 v[66:81], v[218:221], v[102:105], v[66:81]
	v_mfma_f32_32x32x16_bf16 v[82:97], v[222:225], v[102:105], v[82:97]
	v_mfma_f32_32x32x16_bf16 v[66:81], v[226:229], v[106:109], v[66:81]
	v_mfma_f32_32x32x16_bf16 v[82:97], v[230:233], v[106:109], v[82:97]
	v_mfma_f32_32x32x16_bf16 v[66:81], v[238:241], v[110:113], v[66:81]
	v_mfma_f32_32x32x16_bf16 v[82:97], v[242:245], v[110:113], v[82:97]
	s_setprio 0
	v_add_u32_e32 v204, s12, v184
	v_add_u32_e32 v208, s12, v188
	v_add_u32_e32 v205, s12, v185
	v_add_u32_e32 v209, s12, v189
	v_add_u32_e32 v206, s12, v186
	v_add_u32_e32 v210, s12, v190
	v_add_u32_e32 v207, s12, v187
	v_add_u32_e32 v211, s12, v191
	ds_read_b64_tr_b16 v[218:219], v204 offset:16384
	ds_read_b64_tr_b16 v[220:221], v208 offset:16384
	ds_read_b64_tr_b16 v[222:223], v205 offset:16384
	ds_read_b64_tr_b16 v[224:225], v209 offset:16384
	ds_read_b64_tr_b16 v[226:227], v206 offset:16384
	ds_read_b64_tr_b16 v[228:229], v210 offset:16384
	ds_read_b64_tr_b16 v[230:231], v207 offset:16384
	ds_read_b64_tr_b16 v[232:233], v211 offset:16384
	ds_read_b64_tr_b16 v[238:239], v204 offset:20480
	ds_read_b64_tr_b16 v[240:241], v208 offset:20480
	ds_read_b64_tr_b16 v[242:243], v205 offset:20480
	ds_read_b64_tr_b16 v[244:245], v209 offset:20480
	ds_read_b64_tr_b16 v[246:247], v206 offset:20480
	ds_read_b64_tr_b16 v[248:249], v210 offset:20480
	ds_read_b64_tr_b16 v[212:213], v207 offset:20480
	ds_read_b64_tr_b16 v[214:215], v211 offset:20480
	s_add_i32 s22, s22, 63
	s_cmp_le_u32 s22, s62
	s_cbranch_scc1 .LBB0_524
	v_add_u32_e32 v120, s67, v198
	v_cmp_lt_u32_e32 vcc, v120, v155
	v_add_u32_e32 v175, 2, v120
	s_nop 2
	v_cndmask_b32_e32 v67, v197, v67, vcc
	v_cmp_le_u32_e32 vcc, v120, v155
	s_nop 1
	v_cndmask_b32_e32 v66, v197, v66, vcc
	v_cmp_lt_i32_e32 vcc, v120, v157
	s_nop 1
	v_cndmask_b32_e32 v83, v197, v83, vcc
	v_cmp_le_i32_e32 vcc, v120, v157
	s_nop 1
	v_cndmask_b32_e32 v82, v197, v82, vcc
	v_cmp_le_u32_e32 vcc, v175, v155
	s_nop 1
	v_cndmask_b32_e32 v68, v197, v68, vcc
	v_cmp_le_i32_e32 vcc, v175, v157
	v_add_u32_e32 v175, 3, v120
	s_nop 0
	v_cndmask_b32_e32 v84, v197, v84, vcc
	v_cmp_le_u32_e32 vcc, v175, v155
	s_nop 1
	v_cndmask_b32_e32 v69, v197, v69, vcc
	v_cmp_le_i32_e32 vcc, v175, v157
	v_add_u32_e32 v175, 8, v120
	s_nop 0
	v_cndmask_b32_e32 v85, v197, v85, vcc
	v_cmp_le_u32_e32 vcc, v175, v155
	s_nop 1
	v_cndmask_b32_e32 v70, v197, v70, vcc
	v_cmp_le_i32_e32 vcc, v175, v157
	v_add_u32_e32 v175, 9, v120
	s_nop 0
	v_cndmask_b32_e32 v86, v197, v86, vcc
	v_cmp_le_u32_e32 vcc, v175, v155
	s_nop 1
	v_cndmask_b32_e32 v71, v197, v71, vcc
	v_cmp_le_i32_e32 vcc, v175, v157
	v_add_u32_e32 v175, 10, v120
	s_nop 0
	v_cndmask_b32_e32 v87, v197, v87, vcc
	v_cmp_le_u32_e32 vcc, v175, v155
	s_nop 1
	v_cndmask_b32_e32 v72, v197, v72, vcc
	v_cmp_le_i32_e32 vcc, v175, v157
	v_add_u32_e32 v175, 11, v120
	s_nop 0
	v_cndmask_b32_e32 v88, v197, v88, vcc
	v_cmp_le_u32_e32 vcc, v175, v155
	s_nop 1
	v_cndmask_b32_e32 v73, v197, v73, vcc
	v_cmp_le_i32_e32 vcc, v175, v157
	v_add_u32_e32 v175, 16, v120
	s_nop 0
	v_cndmask_b32_e32 v89, v197, v89, vcc
	v_cmp_le_u32_e32 vcc, v175, v155
	s_nop 1
	v_cndmask_b32_e32 v74, v197, v74, vcc
	v_cmp_le_i32_e32 vcc, v175, v157
	v_add_u32_e32 v175, 17, v120
	s_nop 0
	v_cndmask_b32_e32 v90, v197, v90, vcc
	v_cmp_le_u32_e32 vcc, v175, v155
	s_nop 1
	v_cndmask_b32_e32 v75, v197, v75, vcc
	v_cmp_le_i32_e32 vcc, v175, v157
	v_add_u32_e32 v175, 18, v120
	s_nop 0
	v_cndmask_b32_e32 v91, v197, v91, vcc
	v_cmp_le_u32_e32 vcc, v175, v155
	s_nop 1
	v_cndmask_b32_e32 v76, v197, v76, vcc
	v_cmp_le_i32_e32 vcc, v175, v157
	v_add_u32_e32 v175, 19, v120
	s_nop 0
	v_cndmask_b32_e32 v92, v197, v92, vcc
	v_cmp_le_u32_e32 vcc, v175, v155
	s_nop 1
	v_cndmask_b32_e32 v77, v197, v77, vcc
	v_cmp_le_i32_e32 vcc, v175, v157
	v_add_u32_e32 v175, 24, v120
	s_nop 0
	v_cndmask_b32_e32 v93, v197, v93, vcc
	v_cmp_le_u32_e32 vcc, v175, v155
	s_nop 1
	v_cndmask_b32_e32 v78, v197, v78, vcc
	v_cmp_le_i32_e32 vcc, v175, v157
	v_add_u32_e32 v175, 25, v120
	s_nop 0
	v_cndmask_b32_e32 v94, v197, v94, vcc
	v_cmp_le_u32_e32 vcc, v175, v155
	s_nop 1
	v_cndmask_b32_e32 v79, v197, v79, vcc
	v_cmp_le_i32_e32 vcc, v175, v157
	v_add_u32_e32 v175, 26, v120
	v_add_u32_e32 v120, 27, v120
	v_cndmask_b32_e32 v95, v197, v95, vcc
	v_cmp_le_u32_e32 vcc, v175, v155
	s_nop 1
	v_cndmask_b32_e32 v80, v197, v80, vcc
	v_cmp_le_i32_e32 vcc, v175, v157
	s_nop 1
	v_cndmask_b32_e32 v96, v197, v96, vcc
	v_cmp_le_u32_e32 vcc, v120, v155
	s_nop 1
	v_cndmask_b32_e32 v81, v197, v81, vcc
	v_cmp_le_i32_e32 vcc, v120, v157
	s_nop 1
	v_cndmask_b32_e32 v97, v197, v97, vcc
; __device__ __forceinline__ void attn_unit(Frame& F, int b, int h, int qb, const bf16* QKVU, bf16* ATT, float lam, const float* subln_g, const unsigned* kmaxw) {
;     ...
;             float mx = fmaxf(fmaxf(p0[0], p0[1]), p1[0]), mx2 = fmaxf(fmaxf(p0[2], p0[3]), p1[1]);
;             mx = fmaxf(fmaxf(mx, p1[2]), p1[3]);
; #pragma unroll
;             for (int r = 4; r < 16; r += 4) { mx = fmaxf(fmaxf(mx, p0[r]), p0[r + 1]); mx2 = fmaxf(fmaxf(mx2, p0[r + 2]), p0[r + 3]); mx = fmaxf(fmaxf(mx, p1[r]), p1[r + 1]); mx2 = fmaxf(fmaxf(mx2, p1[r + 2]), p1[r + 3]); }
;             mx = fmaxf(mx, mx2);
;             mx = fmaxf(mx, __shfl_xor(mx, 32));
;             bool sub = false; float delta = 0.f;
;             if (!started) { delta = mx; started = true; sub = true; }
;             else if (__any(mx > THR_RESC)) { delta = fmaxf(mx, 0.f); sub = true; const float f = __builtin_amdgcn_exp2f(-delta); l_sum *= f;
; #pragma unroll
;                 for (int c = 0; c < 4; ++c)
; #pragma unroll
;                     for (int r = 0; r < 16; ++r) o[c][r] *= f; }
.LBB0_524:
	s_nop 5
	v_max_f32_e32 v120, v67, v67
	v_max_f32_e32 v175, v66, v66
	v_max_f32_e32 v120, v175, v120
	v_max3_f32 v175, v68, v69, v83
	v_max3_f32 v120, v120, v82, v84
	v_max3_f32 v120, v120, v85, v70
	v_max3_f32 v175, v175, v72, v73
	v_max3_f32 v120, v120, v71, v86
	v_max3_f32 v175, v175, v88, v89
	v_max3_f32 v120, v120, v87, v74
	v_max3_f32 v175, v175, v76, v77
	v_max3_f32 v120, v120, v75, v90
	v_max3_f32 v175, v175, v92, v93
	v_max3_f32 v120, v120, v91, v78
	v_max3_f32 v175, v175, v80, v81
	v_max3_f32 v120, v120, v79, v94
	v_max3_f32 v175, v175, v96, v97
	v_max3_f32 v120, v120, v95, v175
	v_mov_b32_e32 v175, v120
	s_andn2_b64 vcc, exec, s[0:1]
	s_mov_b64 s[0:1], -1
	s_nop 0
	v_permlane32_swap_b32_e32 v175, v120
	s_nop 0
	v_max_f32_e32 v120, v120, v175
	s_cbranch_vccnz .LBB0_527
	s_mov_b32 s0, 0x40c00000
	v_cmp_lt_f32_e32 vcc, s0, v120
	s_cbranch_vccz .LBB0_533
	v_max_f32_e32 v120, v120, v120
	v_max_f32_e32 v120, 0, v120
	v_exp_f32_e64 v200, -v120
	s_mov_b64 s[0:1], -1
	v_mul_f32_e32 v64, v64, v200
	v_mul_f32_e32 v65, v65, v200
	v_mul_f32_e32 v62, v62, v200
	v_mul_f32_e32 v63, v63, v200
	v_mul_f32_e32 v60, v60, v200
	v_mul_f32_e32 v61, v61, v200
	v_mul_f32_e32 v58, v58, v200
	v_mul_f32_e32 v59, v59, v200
	v_mul_f32_e32 v56, v56, v200
	v_mul_f32_e32 v57, v57, v200
	v_mul_f32_e32 v54, v54, v200
	v_mul_f32_e32 v55, v55, v200
	v_mul_f32_e32 v52, v52, v200
	v_mul_f32_e32 v53, v53, v200
	v_mul_f32_e32 v50, v50, v200
	v_mul_f32_e32 v51, v51, v200
	v_mul_f32_e32 v48, v48, v200
	v_mul_f32_e32 v49, v49, v200
	v_mul_f32_e32 v46, v46, v200
	v_mul_f32_e32 v47, v47, v200
	v_mul_f32_e32 v44, v44, v200
	v_mul_f32_e32 v45, v45, v200
	v_mul_f32_e32 v42, v42, v200
	v_mul_f32_e32 v43, v43, v200
	v_mul_f32_e32 v40, v40, v200
	v_mul_f32_e32 v41, v41, v200
	v_mul_f32_e32 v38, v38, v200
	v_mul_f32_e32 v39, v39, v200
	v_mul_f32_e32 v36, v36, v200
	v_mul_f32_e32 v37, v37, v200
	v_mul_f32_e32 v34, v34, v200
	v_mul_f32_e32 v35, v35, v200
	v_mul_f32_e32 v16, v16, v200
	v_mul_f32_e32 v17, v17, v200
	v_mul_f32_e32 v14, v14, v200
	v_mul_f32_e32 v15, v15, v200
	v_mul_f32_e32 v12, v12, v200
	v_mul_f32_e32 v13, v13, v200
	v_mul_f32_e32 v10, v10, v200
	v_mul_f32_e32 v11, v11, v200
	v_mul_f32_e32 v8, v8, v200
	v_mul_f32_e32 v9, v9, v200
	v_mul_f32_e32 v6, v6, v200
	v_mul_f32_e32 v7, v7, v200
	v_mul_f32_e32 v4, v4, v200
	v_mul_f32_e32 v5, v5, v200
	v_mul_f32_e32 v2, v2, v200
	v_mul_f32_e32 v3, v3, v200
	v_mul_f32_e32 v32, v32, v200
	v_mul_f32_e32 v33, v33, v200
	v_mul_f32_e32 v30, v30, v200
	v_mul_f32_e32 v31, v31, v200
	v_mul_f32_e32 v28, v28, v200
	v_mul_f32_e32 v29, v29, v200
	v_mul_f32_e32 v26, v26, v200
	v_mul_f32_e32 v27, v27, v200
	v_mul_f32_e32 v24, v24, v200
	v_mul_f32_e32 v25, v25, v200
	v_mul_f32_e32 v22, v22, v200
	v_mul_f32_e32 v23, v23, v200
	v_mul_f32_e32 v20, v20, v200
	v_mul_f32_e32 v21, v21, v200
	v_mul_f32_e32 v18, v18, v200
	v_mul_f32_e32 v19, v19, v200
	v_mul_f32_e32 v177, v177, v200

; #define LAS __attribute__((address_space(3)))
; __device__ __forceinline__ unsigned pk2(float lo, float hi) { unsigned r; asm("v_cvt_pk_bf16_f32 %0, %1, %2" : "=v"(r) : "v"(lo), "v"(hi)); return r; }
; __device__ __forceinline__ void attn_unit(Frame& F, int b, int h, int qb, const bf16* QKVU, bf16* ATT, float lam, const float* subln_g, const unsigned* kmaxw) {
;     ...
;             if (sub) { m_run += delta;
; #pragma unroll
;                 for (int r = 0; r < 16; ++r) { p0[r] -= delta; p1[r] -= delta; } }
;             float ls = 0.f, ls2 = 0.f;
; #pragma unroll
;             for (int r = 0; r < 16; ++r) { p0[r] = __builtin_amdgcn_exp2f(p0[r]); p1[r] = __builtin_amdgcn_exp2f(p1[r]); ls += p0[r]; ls2 += p1[r]; }
;             l_sum += ls + ls2;
;             bf16x8 pf[2][2];
; #pragma unroll
;             for (int s = 0; s < 2; ++s) { v4u a, c;
;                 a.x = pk2(p0[8 * s + 0], p0[8 * s + 1]); a.y = pk2(p0[8 * s + 2], p0[8 * s + 3]); a.z = pk2(p0[8 * s + 4], p0[8 * s + 5]); a.w = pk2(p0[8 * s + 6], p0[8 * s + 7]);
;                 c.x = pk2(p1[8 * s + 0], p1[8 * s + 1]); c.y = pk2(p1[8 * s + 2], p1[8 * s + 3]); c.z = pk2(p1[8 * s + 4], p1[8 * s + 5]); c.w = pk2(p1[8 * s + 6], p1[8 * s + 7]);
;                 pf[0][s] = __builtin_bit_cast(bf16x8, a); pf[1][s] = __builtin_bit_cast(bf16x8, c); }
;             __builtin_amdgcn_s_setprio(1);
; #pragma unroll
;             for (int c = 0; c < 4; ++c) {
;                 const LAS unsigned char* vp0 = Vb + vb[c][0]; const LAS unsigned char* vp1 = Vb + vb[c][1];
; #pragma unroll
;                 for (int blk = 0; blk < 2; ++blk)
; #pragma unroll
;                     for (int s = 0; s < 2; ++s) {
;                         const s16x4 v0 = __builtin_bit_cast(s16x4, __builtin_amdgcn_ds_read_tr16_b64_v4i16((LAS s16x4*)(vp0 + 8192 * blk + 4096 * s)));
;                         const s16x4 v1 = __builtin_bit_cast(s16x4, __builtin_amdgcn_ds_read_tr16_b64_v4i16((LAS s16x4*)(vp1 + 8192 * blk + 4096 * s)));
;                         const bf16x8 vf = (bf16x8){v0[0], v0[1], v0[2], v0[3], v1[0], v1[1], v1[2], v1[3]};
;                         o[c] = __builtin_amdgcn_mfma_f32_32x32x16_bf16(vf, pf[blk][s], o[c], 0, 0, 0);
;                     }
;             }
;             __builtin_amdgcn_s_setprio(0);
;             wdone = __all(cbound + slope2 * (float)(kv0 - 1 - q0) - m_run < -THR_SKIP);
.LBB0_528:
	v_sub_f32_e32 v66, v66, v120
	v_sub_f32_e32 v67, v67, v120
	v_sub_f32_e32 v82, v82, v120
	v_sub_f32_e32 v83, v83, v120
	v_sub_f32_e32 v68, v68, v120
	v_sub_f32_e32 v69, v69, v120
	v_sub_f32_e32 v84, v84, v120
	v_sub_f32_e32 v85, v85, v120
	v_sub_f32_e32 v70, v70, v120
	v_sub_f32_e32 v71, v71, v120
	v_sub_f32_e32 v86, v86, v120
	v_sub_f32_e32 v87, v87, v120
	v_sub_f32_e32 v72, v72, v120
	v_sub_f32_e32 v73, v73, v120
	v_sub_f32_e32 v88, v88, v120
	v_sub_f32_e32 v89, v89, v120
	v_sub_f32_e32 v74, v74, v120
	v_sub_f32_e32 v75, v75, v120
	v_sub_f32_e32 v90, v90, v120
	v_sub_f32_e32 v91, v91, v120
	v_sub_f32_e32 v76, v76, v120
	v_sub_f32_e32 v77, v77, v120
	v_sub_f32_e32 v92, v92, v120
	v_sub_f32_e32 v93, v93, v120
	v_sub_f32_e32 v78, v78, v120
	v_sub_f32_e32 v79, v79, v120
	v_sub_f32_e32 v94, v94, v120
	v_sub_f32_e32 v95, v95, v120
	v_sub_f32_e32 v80, v80, v120
	v_sub_f32_e32 v81, v81, v120
	v_sub_f32_e32 v96, v96, v120
	v_sub_f32_e32 v97, v97, v120
	v_add_f32_e32 v176, v176, v120
.LBB0_529:
	v_exp_f32_e32 v66, v66
	v_exp_f32_e32 v67, v67
	v_exp_f32_e32 v68, v68
	v_exp_f32_e32 v69, v69
	v_exp_f32_e32 v70, v70
	v_exp_f32_e32 v71, v71
	v_exp_f32_e32 v72, v72
	v_exp_f32_e32 v73, v73
	v_add_f32_e32 v200, v66, v67
	v_add_f32_e32 v201, v68, v69
	v_add_f32_e32 v200, v200, v70
	v_add_f32_e32 v201, v201, v71
	v_add_f32_e32 v200, v200, v72
	v_add_f32_e32 v201, v201, v73
	v_cvt_pk_bf16_f32 v66, v66, v67
	v_cvt_pk_bf16_f32 v67, v68, v69
	v_cvt_pk_bf16_f32 v68, v70, v71
	v_cvt_pk_bf16_f32 v69, v72, v73
	s_setprio 1
	s_nop 1
	s_waitcnt lgkmcnt(8)
	v_mfma_f32_32x32x16_bf16 v[50:65], v[218:221], v[66:69], v[50:65]
	v_exp_f32_e32 v74, v74
	v_exp_f32_e32 v75, v75
	v_exp_f32_e32 v76, v76
	v_exp_f32_e32 v77, v77
	v_exp_f32_e32 v78, v78
	v_mfma_f32_32x32x16_bf16 v[34:49], v[222:225], v[66:69], v[34:49]
	v_exp_f32_e32 v79, v79
	v_exp_f32_e32 v80, v80
	v_exp_f32_e32 v81, v81
	v_add_f32_e32 v200, v200, v74
	v_add_f32_e32 v201, v201, v75
	v_mfma_f32_32x32x16_bf16 v[2:17], v[226:229], v[66:69], v[2:17]
	v_add_f32_e32 v200, v200, v76
	v_add_f32_e32 v201, v201, v77
	v_add_f32_e32 v200, v200, v78
	v_add_f32_e32 v201, v201, v79
	v_add_f32_e32 v200, v200, v80
	v_mfma_f32_32x32x16_bf16 v[18:33], v[230:233], v[66:69], v[18:33]
	v_add_f32_e32 v201, v201, v81
	v_cvt_pk_bf16_f32 v74, v74, v75
	v_cvt_pk_bf16_f32 v75, v76, v77
	v_cvt_pk_bf16_f32 v76, v78, v79
	v_cvt_pk_bf16_f32 v77, v80, v81
	ds_read_b64_tr_b16 v[218:219], v204 offset:24576
	ds_read_b64_tr_b16 v[220:221], v208 offset:24576
	ds_read_b64_tr_b16 v[222:223], v205 offset:24576
	ds_read_b64_tr_b16 v[224:225], v209 offset:24576
	ds_read_b64_tr_b16 v[226:227], v206 offset:24576
	ds_read_b64_tr_b16 v[228:229], v210 offset:24576
	ds_read_b64_tr_b16 v[230:231], v207 offset:24576
	ds_read_b64_tr_b16 v[232:233], v211 offset:24576
	s_nop 0
	s_waitcnt lgkmcnt(8)
	v_mfma_f32_32x32x16_bf16 v[50:65], v[238:241], v[74:77], v[50:65]
	v_exp_f32_e32 v82, v82
	v_exp_f32_e32 v83, v83
	v_exp_f32_e32 v84, v84
	v_exp_f32_e32 v85, v85
	v_exp_f32_e32 v86, v86
	v_mfma_f32_32x32x16_bf16 v[34:49], v[242:245], v[74:77], v[34:49]
	v_exp_f32_e32 v87, v87
	v_exp_f32_e32 v88, v88
	v_exp_f32_e32 v89, v89
	v_add_f32_e32 v200, v200, v82
	v_add_f32_e32 v201, v201, v83
	v_mfma_f32_32x32x16_bf16 v[2:17], v[246:249], v[74:77], v[2:17]
	v_add_f32_e32 v200, v200, v84
	v_add_f32_e32 v201, v201, v85
	v_add_f32_e32 v200, v200, v86
	v_add_f32_e32 v201, v201, v87
	v_add_f32_e32 v200, v200, v88
	v_mfma_f32_32x32x16_bf16 v[18:33], v[212:215], v[74:77], v[18:33]
	v_add_f32_e32 v201, v201, v89
	v_cvt_pk_bf16_f32 v70, v82, v83
	v_cvt_pk_bf16_f32 v71, v84, v85
	v_cvt_pk_bf16_f32 v72, v86, v87
	v_cvt_pk_bf16_f32 v73, v88, v89
	ds_read_b64_tr_b16 v[238:239], v204 offset:28672
	ds_read_b64_tr_b16 v[240:241], v208 offset:28672
	ds_read_b64_tr_b16 v[242:243], v205 offset:28672
	ds_read_b64_tr_b16 v[244:245], v209 offset:28672
	ds_read_b64_tr_b16 v[246:247], v206 offset:28672
	ds_read_b64_tr_b16 v[248:249], v210 offset:28672
	ds_read_b64_tr_b16 v[212:213], v207 offset:28672
	ds_read_b64_tr_b16 v[214:215], v211 offset:28672
	s_nop 0
	s_waitcnt lgkmcnt(8)
	v_mfma_f32_32x32x16_bf16 v[50:65], v[218:221], v[70:73], v[50:65]
	v_exp_f32_e32 v90, v90
	v_exp_f32_e32 v91, v91
	v_exp_f32_e32 v92, v92
	v_exp_f32_e32 v93, v93
	v_exp_f32_e32 v94, v94
	v_mfma_f32_32x32x16_bf16 v[34:49], v[222:225], v[70:73], v[34:49]
	v_exp_f32_e32 v95, v95
	v_exp_f32_e32 v96, v96
	v_exp_f32_e32 v97, v97
	v_add_f32_e32 v200, v200, v90
	v_add_f32_e32 v201, v201, v91
	v_mfma_f32_32x32x16_bf16 v[2:17], v[226:229], v[70:73], v[2:17]
	v_add_f32_e32 v200, v200, v92
	v_add_f32_e32 v201, v201, v93
	v_add_f32_e32 v200, v200, v94
	v_add_f32_e32 v201, v201, v95
	v_add_f32_e32 v200, v200, v96
	v_mfma_f32_32x32x16_bf16 v[18:33], v[230:233], v[70:73], v[18:33]
	v_add_f32_e32 v201, v201, v97
	v_cvt_pk_bf16_f32 v78, v90, v91
	v_cvt_pk_bf16_f32 v79, v92, v93
	v_cvt_pk_bf16_f32 v80, v94, v95
	v_cvt_pk_bf16_f32 v81, v96, v97
	s_nop 0
	s_waitcnt lgkmcnt(0)
	v_mfma_f32_32x32x16_bf16 v[50:65], v[238:241], v[78:81], v[50:65]
	v_mfma_f32_32x32x16_bf16 v[34:49], v[242:245], v[78:81], v[34:49]
	v_mfma_f32_32x32x16_bf16 v[2:17], v[246:249], v[78:81], v[2:17]
	v_mfma_f32_32x32x16_bf16 v[18:33], v[212:215], v[78:81], v[18:33]
	v_add_f32_e32 v120, v200, v201
	s_setprio 0
	v_add_f32_e32 v177, v177, v120
	s_add_i32 s0, s64, s67
	v_cvt_f32_i32_e32 v66, s0
	s_mov_b64 s[0:1], -1
	v_fma_f32 v66, v114, v66, v151
	v_sub_f32_e32 v66, v66, v176
	v_cmp_gt_f32_e32 vcc, s60, v66
	s_cmp_eq_u64 vcc, exec
	s_cselect_b64 s[12:13], -1, 0
